# GEMM k-loop: LDS-DMA destination (m0) computed with SALU from per-tile SGPR bases instead of VALU add + v_readfirstlane chains
# speedup vs baseline: 1.0240x; 1.0029x over previous
.LBB0_637:
	s_and_b64 s[2:3], s[8:9], exec
	v_readlane_b32 s2, v255, 26
	v_readlane_b32 s4, v255, 30
	v_readlane_b32 s3, v255, 27
	v_readlane_b32 s5, v255, 31
	s_cselect_b32 s24, s5, s3
	s_cselect_b32 s28, s4, s2
	v_readlane_b32 s2, v255, 24
	v_readlane_b32 s4, v255, 32
	v_readlane_b32 s3, v255, 25
	v_readlane_b32 s5, v255, 33
	s_cselect_b32 s29, s5, s3
	s_cselect_b32 s34, s4, s2
	v_readlane_b32 s2, v255, 23
	v_readlane_b32 s3, v255, 43
	s_cselect_b32 s14, s3, s2
	v_readlane_b32 s2, v255, 39
	s_cselect_b32 s39, s2, 0
	v_readlane_b32 s2, v255, 18
	v_readlane_b32 s3, v255, 40
	s_cselect_b32 s44, s3, s2
	s_lshl_b32 s45, s15, 8
	s_mul_i32 s2, s15, 0xfe
	s_add_i32 s45, s45, s39
	s_lshl_b32 s6, s47, 8
	s_add_i32 s4, s2, -1
	s_cmp_eq_u32 s44, 7
	s_cselect_b64 vcc, -1, 0
	s_and_b64 s[2:3], vcc, exec
	s_cselect_b32 s2, 0, s45
	s_cselect_b32 s40, s4, 0
	s_ashr_i32 s3, s2, 31
	v_mov_b32_e32 v175, v163
	s_mul_i32 s3, s3, s14
	s_mul_hi_u32 s4, s2, s14
	s_ashr_i32 s7, s6, 31
	s_add_i32 s3, s4, s3
	s_waitcnt vmcnt(1)
	v_ashrrev_i32_e32 v10, 6, v175
	s_waitcnt vmcnt(0)
	v_bfe_u32 v14, v175, 3, 3
	s_mul_i32 s2, s2, s14
	s_mul_i32 s4, s7, s14
	s_mul_hi_u32 s5, s6, s14
	v_lshl_or_b32 v6, v10, 5, v14
	s_add_i32 s5, s5, s4
	v_and_b32_e32 v0, 63, v175
	s_lshl_b64 s[2:3], s[2:3], 1
	s_mul_i32 s4, s6, s14
	s_add_u32 s2, s28, s2
	v_lshlrev_b32_e32 v176, 4, v0
	v_add_u32_e32 v0, s40, v6
	s_addc_u32 s3, s24, s3
	s_lshl_b64 s[4:5], s[4:5], 1
	v_med3_i32 v0, v0, 0, v211
	s_add_u32 s4, s34, s4
	v_cndmask_b32_e32 v0, v6, v0, vcc
	s_addc_u32 s5, s29, s5
	v_bfe_u32 v223, v175, 4, 2
	v_mad_u64_u32 v[166:167], s[28:29], v0, s14, 0
	v_xor_b32_e32 v4, v223, v175
	v_ashrrev_i32_e32 v2, 31, v0
	v_mov_b32_e32 v0, v167
	v_mad_u64_u32 v[2:3], s[28:29], v2, s14, v[0:1]
	v_lshlrev_b32_e32 v0, 3, v4
	v_lshlrev_b32_e32 v15, 2, v10
	v_and_b32_e32 v0, 56, v0
	v_lshlrev_b32_e32 v177, 12, v10
	v_lshlrev_b32_e32 v130, 1, v0
	v_ashrrev_i32_e32 v0, 31, v10
	v_or_b32_e32 v17, v176, v177
	v_or_b32_e32 v18, 1, v15
	v_and_b32_e32 v174, 3, v10
	v_mul_lo_u32 v16, v0, s14
	v_readfirstlane_b32 s15, v17
	v_add_u32_e32 v0, 0x8000, v17
	v_lshl_or_b32 v10, v18, 3, v14
	v_mov_b32_e32 v167, v2
	v_mad_u64_u32 v[168:169], s[28:29], v6, s14, 0
	s_mov_b32 m0, s15
	v_readfirstlane_b32 s15, v0
	v_add_u32_e32 v0, s40, v10
	v_lshl_add_u64 v[2:3], v[166:167], 1, s[2:3]
	v_mov_b32_e32 v131, v1
	v_add_u32_e32 v169, v169, v16
	v_med3_i32 v0, v0, 0, v211
	v_lshl_add_u64 v[4:5], v[2:3], 0, v[130:131]
	v_lshl_add_u64 v[6:7], v[168:169], 1, s[4:5]
	v_cndmask_b32_e32 v0, v10, v0, vcc
	v_lshl_add_u64 v[8:9], v[6:7], 0, v[130:131]
	global_load_lds_dwordx4 v[4:5], off
	s_mov_b32 m0, s15
	v_lshrrev_b32_e32 v4, 1, v10
	v_mad_u64_u32 v[170:171], s[28:29], v0, s14, 0
	global_load_lds_dwordx4 v[8:9], off
	v_xor_b32_e32 v8, v4, v175
	v_ashrrev_i32_e32 v4, 31, v0
	v_mov_b32_e32 v0, v171
	v_mad_u64_u32 v[4:5], s[28:29], v4, s14, v[0:1]
	v_lshlrev_b32_e32 v0, 3, v8
	v_lshlrev_b32_e32 v178, 10, v18
	v_mov_b32_e32 v171, v4
	v_and_b32_e32 v0, 56, v0
	v_mad_u64_u32 v[172:173], s[28:29], v10, s14, 0
	v_or_b32_e32 v18, v176, v178
	v_lshl_add_u64 v[4:5], v[170:171], 1, s[2:3]
	v_lshlrev_b32_e32 v132, 1, v0
	v_mov_b32_e32 v133, v1
	v_add_u32_e32 v173, v173, v16
	v_readfirstlane_b32 s15, v18
	v_add_u32_e32 v0, 0x8000, v18
	v_lshl_add_u64 v[8:9], v[4:5], 0, v[132:133]
	v_lshl_add_u64 v[10:11], v[172:173], 1, s[4:5]
	s_mov_b32 m0, s15
	v_readfirstlane_b32 s15, v0
	s_waitcnt lgkmcnt(0)
	v_lshl_add_u64 v[12:13], v[10:11], 0, v[132:133]
	global_load_lds_dwordx4 v[8:9], off
	s_mov_b32 m0, s15
	v_or_b32_e32 v19, 2, v15
	global_load_lds_dwordx4 v[12:13], off
	v_lshl_or_b32 v12, v19, 3, v14
	v_add_u32_e32 v0, s40, v12
	v_med3_i32 v0, v0, 0, v211
	v_cndmask_b32_e32 v0, v12, v0, vcc
	v_lshrrev_b32_e32 v8, 1, v12
	v_mad_u64_u32 v[154:155], s[28:29], v0, s14, 0
	v_xor_b32_e32 v13, v8, v175
	v_ashrrev_i32_e32 v8, 31, v0
	v_mov_b32_e32 v0, v155
	v_mad_u64_u32 v[8:9], s[28:29], v8, s14, v[0:1]
	v_lshlrev_b32_e32 v0, 3, v13
	v_lshlrev_b32_e32 v179, 10, v19
	v_mov_b32_e32 v155, v8
	v_and_b32_e32 v0, 56, v0
	v_or_b32_e32 v19, v176, v179
	v_lshl_add_u64 v[8:9], v[154:155], 1, s[2:3]
	v_lshlrev_b32_e32 v0, 1, v0
	v_readfirstlane_b32 s15, v19
	v_lshl_add_u64 v[8:9], v[8:9], 0, v[0:1]
	v_mad_u64_u32 v[156:157], s[28:29], v12, s14, 0
	s_mov_b32 m0, s15
	v_add_u32_e32 v157, v157, v16
	global_load_lds_dwordx4 v[8:9], off
	v_add_u32_e32 v8, 0x8000, v19
	v_lshl_add_u64 v[12:13], v[156:157], 1, s[4:5]
	v_readfirstlane_b32 s15, v8
	v_lshl_add_u64 v[12:13], v[12:13], 0, v[0:1]
	s_mov_b32 m0, s15
	v_or_b32_e32 v15, 3, v15
	global_load_lds_dwordx4 v[12:13], off
	v_lshl_or_b32 v12, v15, 3, v14
	v_add_u32_e32 v8, s40, v12
	v_med3_i32 v8, v8, 0, v211
	v_cndmask_b32_e32 v8, v12, v8, vcc
	v_lshrrev_b32_e32 v9, 1, v12
	v_mad_u64_u32 v[158:159], s[28:29], v8, s14, 0
	v_xor_b32_e32 v13, v9, v175
	v_ashrrev_i32_e32 v9, 31, v8
	v_mov_b32_e32 v8, v159
	v_mad_u64_u32 v[8:9], s[28:29], v9, s14, v[8:9]
	v_lshlrev_b32_e32 v13, 3, v13
	v_lshlrev_b32_e32 v180, 10, v15
	v_mov_b32_e32 v159, v8
	v_and_b32_e32 v13, 56, v13
	v_or_b32_e32 v14, v176, v180
	v_lshl_add_u64 v[8:9], v[158:159], 1, s[2:3]
	v_lshlrev_b32_e32 v160, 1, v13
	v_mov_b32_e32 v161, v1
	v_readfirstlane_b32 s15, v14
	v_lshl_add_u64 v[8:9], v[8:9], 0, v[160:161]
	v_mad_u64_u32 v[164:165], s[28:29], v12, s14, 0
	s_mov_b32 m0, s15
	v_add_u32_e32 v165, v165, v16
	global_load_lds_dwordx4 v[8:9], off
	v_add_u32_e32 v8, 0x8000, v14
	s_cmpk_gt_u32 s14, 0x7f
	v_lshl_add_u64 v[12:13], v[164:165], 1, s[4:5]
	v_readfirstlane_b32 s15, v8
	s_cselect_b32 s34, 0x80, 0
	v_add_u32_e32 v8, 0x10000, v17
	v_lshl_add_u64 v[12:13], v[12:13], 0, v[160:161]
	s_mov_b32 m0, s15
	v_lshl_add_u64 v[2:3], v[2:3], 0, s[34:35]
	v_readfirstlane_b32 s15, v8
	global_load_lds_dwordx4 v[12:13], off
	v_lshl_add_u64 v[2:3], v[2:3], 0, v[130:131]
	s_mov_b32 m0, s15
	v_mov_b32_e32 v127, 0
	v_mov_b32_e32 v128, 0
	v_mov_b32_e32 v129, 0
	v_mov_b32_e32 v122, 0
	v_mov_b32_e32 v123, 0
	v_mov_b32_e32 v124, 0
	v_mov_b32_e32 v125, 0
	v_mov_b32_e32 v118, 0
	v_mov_b32_e32 v119, 0
	v_mov_b32_e32 v120, 0
	v_mov_b32_e32 v121, 0
	v_mov_b32_e32 v114, 0
	v_mov_b32_e32 v115, 0
	v_mov_b32_e32 v116, 0
	v_mov_b32_e32 v117, 0
	v_mov_b32_e32 v110, 0
	v_mov_b32_e32 v111, 0
	v_mov_b32_e32 v112, 0
	v_mov_b32_e32 v113, 0
	v_mov_b32_e32 v106, 0
	v_mov_b32_e32 v107, 0
	v_mov_b32_e32 v108, 0
	v_mov_b32_e32 v109, 0
	v_mov_b32_e32 v102, 0
	v_mov_b32_e32 v103, 0
	v_mov_b32_e32 v104, 0
	v_mov_b32_e32 v105, 0
	v_mov_b32_e32 v98, 0
	v_mov_b32_e32 v99, 0
	v_mov_b32_e32 v100, 0
	v_mov_b32_e32 v101, 0
	v_mov_b32_e32 v94, 0
	v_mov_b32_e32 v95, 0
	v_mov_b32_e32 v96, 0
	v_mov_b32_e32 v97, 0
	v_mov_b32_e32 v90, 0
	v_mov_b32_e32 v91, 0
	v_mov_b32_e32 v92, 0
	v_mov_b32_e32 v93, 0
	v_mov_b32_e32 v86, 0
	v_mov_b32_e32 v87, 0
	v_mov_b32_e32 v88, 0
	v_mov_b32_e32 v89, 0
	v_mov_b32_e32 v82, 0
	v_mov_b32_e32 v83, 0
	v_mov_b32_e32 v84, 0
	v_mov_b32_e32 v85, 0
	v_mov_b32_e32 v78, 0
	v_mov_b32_e32 v79, 0
	v_mov_b32_e32 v80, 0
	v_mov_b32_e32 v81, 0
	v_mov_b32_e32 v74, 0
	v_mov_b32_e32 v75, 0
	v_mov_b32_e32 v76, 0
	v_mov_b32_e32 v77, 0
	v_mov_b32_e32 v70, 0
	v_mov_b32_e32 v71, 0
	v_mov_b32_e32 v72, 0
	v_mov_b32_e32 v73, 0
	v_mov_b32_e32 v66, 0
	v_mov_b32_e32 v67, 0
	v_mov_b32_e32 v68, 0
	v_mov_b32_e32 v69, 0
	v_mov_b32_e32 v62, 0
	v_mov_b32_e32 v63, 0
	v_mov_b32_e32 v64, 0
	v_mov_b32_e32 v65, 0
	v_mov_b32_e32 v58, 0
	v_mov_b32_e32 v59, 0
	v_mov_b32_e32 v60, 0
	v_mov_b32_e32 v61, 0
	v_mov_b32_e32 v54, 0
	v_mov_b32_e32 v55, 0
	v_mov_b32_e32 v56, 0
	v_mov_b32_e32 v57, 0
	v_mov_b32_e32 v50, 0
	v_mov_b32_e32 v51, 0
	v_mov_b32_e32 v52, 0
	v_mov_b32_e32 v53, 0
	v_mov_b32_e32 v46, 0
	v_mov_b32_e32 v47, 0
	v_mov_b32_e32 v48, 0
	v_mov_b32_e32 v49, 0
	v_mov_b32_e32 v42, 0
	v_mov_b32_e32 v43, 0
	v_mov_b32_e32 v44, 0
	v_mov_b32_e32 v45, 0
	v_mov_b32_e32 v34, 0
	v_mov_b32_e32 v35, 0
	v_mov_b32_e32 v36, 0
	v_mov_b32_e32 v37, 0
	v_mov_b32_e32 v30, 0
	v_mov_b32_e32 v31, 0
	v_mov_b32_e32 v32, 0
	v_mov_b32_e32 v33, 0
	v_mov_b32_e32 v38, 0
	v_mov_b32_e32 v39, 0
	v_mov_b32_e32 v40, 0
	v_mov_b32_e32 v41, 0
	v_mov_b32_e32 v26, 0
	v_mov_b32_e32 v27, 0
	v_mov_b32_e32 v28, 0
	v_mov_b32_e32 v29, 0
	v_mov_b32_e32 v22, 0
	v_mov_b32_e32 v23, 0
	v_mov_b32_e32 v24, 0
	v_mov_b32_e32 v25, 0
	v_mov_b32_e32 v19, 0
	v_mov_b32_e32 v20, 0
	v_mov_b32_e32 v21, 0
	v_mov_b32_e32 v14, 0
	v_mov_b32_e32 v15, 0
	v_mov_b32_e32 v16, 0
	v_mov_b32_e32 v12, 0
	v_mov_b32_e32 v13, 0
	s_waitcnt vmcnt(0)
	s_waitcnt vmcnt(0) lgkmcnt(0)
	s_barrier
	global_load_lds_dwordx4 v[2:3], off
	v_add_u32_e32 v2, 0x18000, v17
	v_lshl_add_u64 v[6:7], v[6:7], 0, s[34:35]
	v_readfirstlane_b32 s15, v2
	v_lshl_add_u64 v[6:7], v[6:7], 0, v[130:131]
	s_mov_b32 m0, s15
	v_lshl_add_u64 v[2:3], v[4:5], 0, s[34:35]
	global_load_lds_dwordx4 v[6:7], off
	v_add_u32_e32 v6, 0x10000, v18
	v_lshl_add_u64 v[2:3], v[2:3], 0, v[132:133]
	v_readfirstlane_b32 s15, v6
	s_mov_b32 m0, s15
	v_lshl_add_u64 v[4:5], v[10:11], 0, s[34:35]
	global_load_lds_dwordx4 v[2:3], off
	v_add_u32_e32 v2, 0x18000, v18
	v_lshl_add_u64 v[4:5], v[4:5], 0, v[132:133]
	v_readfirstlane_b32 s15, v2
	s_mov_b32 m0, s15
	v_and_b32_e32 v134, 15, v175
	global_load_lds_dwordx4 v[4:5], off
	v_ashrrev_i32_e32 v2, 1, v175
	s_movk_i32 s15, 0xff80
	v_mov_b32_e32 v5, 0
	v_and_or_b32 v225, v2, s15, v134
	v_lshlrev_b32_e32 v224, 6, v174
	s_cmp_lt_u32 s14, 64
	v_readlane_b32 s51, v255, 37
	v_readlane_b32 s52, v255, 38
	s_cbranch_scc1 .Lgemm_skip_zero_a
	v_lshrrev_b32_e32 v10, 1, v134
	v_or_b32_e32 v2, v224, v134
	v_lshlrev_b32_e32 v182, 7, v2
	v_xor_b32_e32 v2, v223, v10
	v_lshlrev_b32_e32 v181, 7, v225
	v_lshlrev_b32_e32 v183, 4, v2
	v_or_b32_e32 v11, v181, v183
	v_or_b32_e32 v244, v182, v183
	v_lshl_add_u64 v[2:3], s[4:5], 0, v[132:133]
	v_lshl_add_u64 v[4:5], s[2:3], 0, v[132:133]
	v_lshl_add_u64 v[6:7], s[4:5], 0, v[130:131]
	v_lshl_add_u64 v[8:9], s[2:3], 0, v[130:131]
	ds_read_b128 v[150:153], v11
	ds_read_b128 v[146:149], v11 offset:2048
	ds_read_b128 v[142:145], v244 offset:32768
	ds_read_b128 v[138:141], v244 offset:34816
	ds_read_b128 v[134:137], v244 offset:36864
	ds_read_b128 v[200:203], v11 offset:4096
	ds_read_b128 v[130:133], v244 offset:38912
	ds_read_b128 v[236:239], v11 offset:6144
	s_lshr_b32 s14, s14, 6
	v_bitop3_b32 v10, v223, v10, 4 bitop3:0x36
	v_mov_b32_e32 v126, 0
	s_add_i32 s15, s14, -1
	v_lshlrev_b32_e32 v184, 4, v10
	v_lshl_add_u64 v[166:167], v[166:167], 1, v[8:9]
	v_lshl_add_u64 v[168:169], v[168:169], 1, v[6:7]
	v_lshl_add_u64 v[170:171], v[170:171], 1, v[4:5]
	v_lshl_add_u64 v[172:173], v[172:173], 1, v[2:3]
	s_mov_b32 s24, 0
	s_mov_b32 s28, 0
	v_readfirstlane_b32 s100, v179
	v_readfirstlane_b32 s101, v180
	v_readfirstlane_b32 s32, v178
	v_readfirstlane_b32 s41, v177
	s_lshl_b32 s32, s32, 16
	s_or_b32 s32, s32, s41
	v_mov_b32_e32 v18, v126
	v_mov_b32_e32 v17, v126
	v_mov_b32_e32 v10, v126
	v_mov_b32_e32 v11, v126
	v_mov_b32_e32 v6, v126
	v_mov_b32_e32 v7, v126
	v_mov_b32_e32 v8, v126
	v_mov_b32_e32 v9, v126
	v_mov_b32_e32 v2, v126
	v_mov_b32_e32 v3, v126
	v_mov_b32_e32 v4, v126
	v_mov_b32_e32 v5, v126
.LBB0_639:
	s_add_i32 s41, s28, 1
	s_cmp_lt_u32 s41, s14
	s_cselect_b32 s29, s41, s28
	s_and_b32 s46, s24, 0x10000
	s_lshl_b32 s34, s29, 6
	s_xor_b32 s50, s46, 0x10000
	s_lshl_b64 s[42:43], s[34:35], 1
	s_add_u32 s48, s2, s42
	s_addc_u32 s49, s3, s43
	s_add_u32 s42, s4, s42
	v_add_u32_e32 v185, s46, v181
	s_waitcnt lgkmcnt(5)
	v_mfma_f32_16x16x32_bf16 v[126:129], v[142:145], v[150:153], v[126:129]
	s_addc_u32 s43, s5, s43
	v_lshl_add_u64 v[186:187], v[154:155], 1, s[48:49]
	v_mov_b32_e32 v161, v1
	v_add_u32_e32 v227, v185, v183
	v_mfma_f32_16x16x32_bf16 v[110:113], v[142:145], v[146:149], v[110:113]
	v_lshl_add_u64 v[186:187], v[186:187], 0, v[0:1]
	v_lshl_add_u64 v[240:241], v[156:157], 1, s[42:43]
	s_add_i32 m0, s50, s100
	s_waitcnt lgkmcnt(4)
	v_mfma_f32_16x16x32_bf16 v[122:125], v[138:141], v[150:153], v[122:125]
	s_add_i32 s28, s28, 2
	s_min_i32 s28, s28, s15
	s_lshl_b32 s28, s28, 6
	v_mfma_f32_16x16x32_bf16 v[106:109], v[138:141], v[146:149], v[106:109]
	v_lshl_add_u64 v[240:241], v[240:241], 0, v[0:1]
	global_load_lds_dwordx4 v[186:187], off
	s_add_i32 m0, m0, 0x8000
	s_waitcnt lgkmcnt(3)
	v_mfma_f32_16x16x32_bf16 v[118:121], v[134:137], v[150:153], v[118:121]
	v_lshl_add_u64 v[244:245], v[158:159], 1, s[48:49]
	v_lshl_add_u64 v[246:247], v[164:165], 1, s[42:43]
	v_mfma_f32_16x16x32_bf16 v[102:105], v[134:137], v[146:149], v[102:105]
	global_load_lds_dwordx4 v[240:241], off
	s_add_i32 m0, s50, s101
	s_waitcnt lgkmcnt(1)
	v_mfma_f32_16x16x32_bf16 v[114:117], v[130:133], v[150:153], v[114:117]
	ds_read_b128 v[150:153], v227 offset:8192
	v_mfma_f32_16x16x32_bf16 v[98:101], v[130:133], v[146:149], v[98:101]
	ds_read_b128 v[146:149], v227 offset:10240
	v_lshl_add_u64 v[244:245], v[244:245], 0, v[160:161]
	v_lshl_add_u64 v[246:247], v[246:247], 0, v[160:161]
	v_mfma_f32_16x16x32_bf16 v[94:97], v[142:145], v[200:203], v[94:97]
	v_mfma_f32_16x16x32_bf16 v[90:93], v[138:141], v[200:203], v[90:93]
	global_load_lds_dwordx4 v[244:245], off
	s_add_i32 m0, m0, 0x8000
	v_mfma_f32_16x16x32_bf16 v[86:89], v[134:137], v[200:203], v[86:89]
	v_mfma_f32_16x16x32_bf16 v[82:85], v[130:133], v[200:203], v[82:85]
	ds_read_b128 v[200:203], v227 offset:12288
	v_bitop3_b32 v243, s24, v182, v212 bitop3:0xce
	s_waitcnt lgkmcnt(3)
	v_mfma_f32_16x16x32_bf16 v[78:81], v[142:145], v[236:239], v[78:81]
	global_load_lds_dwordx4 v[246:247], off
	v_add_u32_e32 v233, v243, v183
	v_mfma_f32_16x16x32_bf16 v[74:77], v[138:141], v[236:239], v[74:77]
	v_mfma_f32_16x16x32_bf16 v[70:73], v[134:137], v[236:239], v[70:73]
	v_or_b32_e32 v228, s46, v182
	s_ashr_i32 s29, s28, 31
	v_mfma_f32_16x16x32_bf16 v[66:69], v[130:133], v[236:239], v[66:69]
	ds_read_b128 v[236:239], v227 offset:14336
	s_waitcnt lgkmcnt(3)
	v_mfma_f32_16x16x32_bf16 v[62:65], v[142:145], v[150:153], v[62:65]
	v_add3_u32 v234, s50, v181, v183
	v_add_u32_e32 v228, v228, v184
	v_mfma_f32_16x16x32_bf16 v[58:61], v[138:141], v[150:153], v[58:61]
	v_add_u32_e32 v229, v185, v184
	v_mfma_f32_16x16x32_bf16 v[54:57], v[134:137], v[150:153], v[54:57]
	v_mfma_f32_16x16x32_bf16 v[50:53], v[130:133], v[150:153], v[50:53]
	ds_read_b128 v[150:153], v229
	s_waitcnt lgkmcnt(3)
	v_mfma_f32_16x16x32_bf16 v[46:49], v[142:145], v[146:149], v[46:49]
	v_mfma_f32_16x16x32_bf16 v[42:45], v[138:141], v[146:149], v[42:45]
	v_mfma_f32_16x16x32_bf16 v[34:37], v[134:137], v[146:149], v[34:37]
	v_mfma_f32_16x16x32_bf16 v[30:33], v[130:133], v[146:149], v[30:33]
	ds_read_b128 v[146:149], v229 offset:2048
	s_waitcnt lgkmcnt(3)
	v_mfma_f32_16x16x32_bf16 v[38:41], v[142:145], v[200:203], v[38:41]
	s_waitcnt lgkmcnt(2)
	v_mfma_f32_16x16x32_bf16 v[14:17], v[142:145], v[236:239], v[14:17]
	ds_read_b128 v[142:145], v228 offset:32768
	v_mfma_f32_16x16x32_bf16 v[26:29], v[138:141], v[200:203], v[26:29]
	v_mfma_f32_16x16x32_bf16 v[10:13], v[138:141], v[236:239], v[10:13]
	ds_read_b128 v[138:141], v228 offset:34816
	v_mfma_f32_16x16x32_bf16 v[22:25], v[134:137], v[200:203], v[22:25]
	v_mfma_f32_16x16x32_bf16 v[6:9], v[134:137], v[236:239], v[6:9]
	ds_read_b128 v[134:137], v228 offset:36864
	v_mfma_f32_16x16x32_bf16 v[18:21], v[130:133], v[200:203], v[18:21]
	ds_read_b128 v[200:203], v229 offset:4096
	v_mfma_f32_16x16x32_bf16 v[2:5], v[130:133], v[236:239], v[2:5]
	ds_read_b128 v[130:133], v228 offset:38912
	ds_read_b128 v[236:239], v229 offset:6144
	s_waitcnt lgkmcnt(5)
	v_mfma_f32_16x16x32_bf16 v[126:129], v[142:145], v[150:153], v[126:129]
	v_mfma_f32_16x16x32_bf16 v[110:113], v[142:145], v[146:149], v[110:113]
	s_waitcnt lgkmcnt(4)
	v_mfma_f32_16x16x32_bf16 v[122:125], v[138:141], v[150:153], v[122:125]
	v_mfma_f32_16x16x32_bf16 v[106:109], v[138:141], v[146:149], v[106:109]
	s_waitcnt lgkmcnt(3)
	v_mfma_f32_16x16x32_bf16 v[118:121], v[134:137], v[150:153], v[118:121]
	v_mfma_f32_16x16x32_bf16 v[102:105], v[134:137], v[146:149], v[102:105]
	s_waitcnt lgkmcnt(1)
	v_mfma_f32_16x16x32_bf16 v[114:117], v[130:133], v[150:153], v[114:117]
	ds_read_b128 v[150:153], v229 offset:8192
	v_mfma_f32_16x16x32_bf16 v[98:101], v[130:133], v[146:149], v[98:101]
	ds_read_b128 v[146:149], v229 offset:10240
	v_mfma_f32_16x16x32_bf16 v[94:97], v[142:145], v[200:203], v[94:97]
	v_mfma_f32_16x16x32_bf16 v[90:93], v[138:141], v[200:203], v[90:93]
	v_mfma_f32_16x16x32_bf16 v[86:89], v[134:137], v[200:203], v[86:89]
	v_mfma_f32_16x16x32_bf16 v[82:85], v[130:133], v[200:203], v[82:85]
	ds_read_b128 v[200:203], v229 offset:12288
	s_waitcnt lgkmcnt(3)
	v_mfma_f32_16x16x32_bf16 v[78:81], v[142:145], v[236:239], v[78:81]
	v_mfma_f32_16x16x32_bf16 v[74:77], v[138:141], v[236:239], v[74:77]
	v_mfma_f32_16x16x32_bf16 v[70:73], v[134:137], v[236:239], v[70:73]
	s_lshl_b64 s[28:29], s[28:29], 1
	s_and_b32 m0, s32, 0xffff
	v_mfma_f32_16x16x32_bf16 v[66:69], v[130:133], v[236:239], v[66:69]
	ds_read_b128 v[236:239], v229 offset:14336
	s_add_i32 m0, m0, s46
	s_waitcnt lgkmcnt(3)
	v_mfma_f32_16x16x32_bf16 v[62:65], v[142:145], v[150:153], v[62:65]
	v_mfma_f32_16x16x32_bf16 v[58:61], v[138:141], v[150:153], v[58:61]
	v_mfma_f32_16x16x32_bf16 v[54:57], v[134:137], v[150:153], v[54:57]
	s_waitcnt vmcnt(0)
	v_mfma_f32_16x16x32_bf16 v[50:53], v[130:133], v[150:153], v[50:53]
	s_waitcnt vmcnt(0) lgkmcnt(0)
	s_barrier
	ds_read_b128 v[150:153], v234
	v_mfma_f32_16x16x32_bf16 v[46:49], v[142:145], v[146:149], v[46:49]
	v_lshl_add_u64 v[240:241], v[166:167], 0, s[28:29]
	v_lshl_add_u64 v[244:245], v[168:169], 0, s[28:29]
	global_load_lds_dwordx4 v[240:241], off
	s_add_i32 m0, m0, 0x8000
	v_mfma_f32_16x16x32_bf16 v[42:45], v[138:141], v[146:149], v[42:45]
	v_mfma_f32_16x16x32_bf16 v[34:37], v[134:137], v[146:149], v[34:37]
	global_load_lds_dwordx4 v[244:245], off
	s_lshr_b32 m0, s32, 16
	v_mfma_f32_16x16x32_bf16 v[30:33], v[130:133], v[146:149], v[30:33]
	ds_read_b128 v[146:149], v234 offset:2048
	v_lshl_add_u64 v[246:247], v[170:171], 0, s[28:29]
	v_lshl_add_u64 v[242:243], v[172:173], 0, s[28:29]
	s_add_i32 m0, m0, s46
	v_mfma_f32_16x16x32_bf16 v[38:41], v[142:145], v[200:203], v[38:41]
	v_mfma_f32_16x16x32_bf16 v[14:17], v[142:145], v[236:239], v[14:17]
	ds_read_b128 v[142:145], v233 offset:32768
	global_load_lds_dwordx4 v[246:247], off
	s_add_i32 m0, m0, 0x8000
	v_mfma_f32_16x16x32_bf16 v[26:29], v[138:141], v[200:203], v[26:29]
	v_mfma_f32_16x16x32_bf16 v[10:13], v[138:141], v[236:239], v[10:13]
	ds_read_b128 v[138:141], v233 offset:34816
	global_load_lds_dwordx4 v[242:243], off
	v_mfma_f32_16x16x32_bf16 v[22:25], v[134:137], v[200:203], v[22:25]
	v_mfma_f32_16x16x32_bf16 v[6:9], v[134:137], v[236:239], v[6:9]
	ds_read_b128 v[134:137], v233 offset:36864
	v_mfma_f32_16x16x32_bf16 v[18:21], v[130:133], v[200:203], v[18:21]
	ds_read_b128 v[200:203], v234 offset:4096
	v_mfma_f32_16x16x32_bf16 v[2:5], v[130:133], v[236:239], v[2:5]
	ds_read_b128 v[130:133], v233 offset:38912
	ds_read_b128 v[236:239], v234 offset:6144
	s_add_i32 s24, s24, 0x10000
	s_cmp_eq_u32 s14, s41
	s_mov_b32 s28, s41
	s_cbranch_scc0 .LBB0_639
